# P9: half of the CUs (blockIdx bit 3) run their split-K slice unit before the full prompt tile, staggering the epilogue store bursts
# baseline (speedup 1.0000x reference)
.LBB0_1580:
	v_readlane_b32 s0, v245, 35
	s_cmp_lt_i32 s0, 10
	v_readlane_b32 s1, v245, 36
	s_cselect_b64 s[8:9], -1, 0
	s_and_b64 s[0:1], s[8:9], s[6:7]
	s_andn2_b64 vcc, exec, s[0:1]
	s_cbranch_vccnz .LBB0_1620
	s_bfe_u32 s77, s96, 0x10003
	s_lshl_b32 s78, s77, 8
	s_add_i32 s78, s78, s96
	s_cmpk_gt_i32 s78, 0x1ff
	v_readfirstlane_b32 s20, v0
	s_cbranch_scc1 .LBB0_1620
	s_add_i32 s0, s78, 0xffffff00
	s_cmpk_lt_i32 s78, 0x100
	s_cselect_b64 s[6:7], -1, 0
	s_and_b64 vcc, s[6:7], exec
	s_cselect_b32 s0, s78, s0
	s_ashr_i32 s14, s0, 5
	s_mov_b32 s12, 0
	s_mov_b32 s10, -1
	s_cbranch_vccnz .LBB0_1588
	s_cmp_gt_i32 s14, 5
	s_cbranch_scc0 .LBB0_1585
	s_lshl_b32 s1, s14, 2
	s_add_i32 s12, s1, 12
	s_cbranch_execz .LBB0_1586
	s_branch .LBB0_1587

.LBB0_1588:
	s_and_b32 s1, s0, 7
	s_ashr_i32 s2, s0, 3
	s_lshl_b32 s0, s1, 3
	s_and_b32 s3, s2, 7
	s_or_b32 s3, s0, s3
	s_or_b32 s4, s1, 64
	s_and_b64 s[0:1], s[6:7], exec
	s_cselect_b32 s48, s3, s4
	s_ashr_i32 s3, s78, 6
	s_and_b32 s2, s2, 3
	s_and_b64 s[0:1], s[6:7], exec
	s_cselect_b32 s49, s3, s2
	s_add_u32 s0, s34, 0x1b500000
	s_addc_u32 s1, s35, 0
	v_lshlrev_b32_e32 v1, 4, v0
	v_and_b32_e32 v2, 32, v0
	s_add_u32 s2, s34, 0x1500000
	v_bfe_u32 v3, v0, 2, 4
	v_bitop3_b32 v10, v1, v2, 48 bitop3:0x6c
	v_lshrrev_b32_e32 v2, 3, v0
	s_addc_u32 s3, s35, 0
	v_and_or_b32 v4, v2, 48, v3
	v_or_b32_e32 v2, 64, v2
	s_movk_i32 s4, 0x70
	s_lshr_b32 s18, s20, 6
	s_ashr_i32 s13, s12, 31
	s_lshr_b32 s11, s20, 8
	v_and_or_b32 v2, v2, s4, v3
	s_lshl_b32 s4, s18, 10
	s_lshl_b64 s[12:13], s[12:13], 7
	s_mul_i32 s5, s48, 0x160000
	s_add_u32 s15, s0, s5
	s_addc_u32 s19, s1, 0
	s_mul_i32 s16, s49, 0x160000
	s_mul_hi_i32 s5, s49, 0x160000
	s_add_u32 s16, s2, s16
	s_addc_u32 s5, s3, s5
	v_and_b32_e32 v11, 64, v0
	s_add_u32 s54, s16, s12
	v_or_b32_e32 v1, v10, v11
	v_mul_u32_u24_e32 v12, 0x1600, v4
	s_addc_u32 s55, s5, s13
	s_add_i32 s5, s4, 0
	v_or_b32_e32 v186, v12, v1
	s_add_i32 m0, s5, 0x10000
	v_mul_u32_u24_e32 v13, 0x1600, v2
	global_load_lds_dwordx4 v186, s[54:55]
	s_add_i32 m0, s5, 0x12000
	v_or_b32_e32 v188, v13, v1
	s_add_u32 s16, s54, 0xb0000
	global_load_lds_dwordx4 v188, s[54:55]
	s_addc_u32 s17, s55, 0
	s_add_i32 m0, s5, 0x14000
	s_load_dword s60, s[60:61], 0xd0
	global_load_lds_dwordx4 v186, s[16:17]
	s_add_i32 m0, s5, 0x16000
	s_add_u32 s52, s15, s12
	s_addc_u32 s53, s19, s13
	s_add_i32 s33, s5, 0x2000
	global_load_lds_dwordx4 v188, s[16:17]
	s_mov_b32 m0, s5
	s_add_u32 s12, s52, 0xb0000
	global_load_lds_dwordx4 v186, s[52:53]
	s_mov_b32 m0, s33
	s_addc_u32 s13, s53, 0
	s_add_i32 s58, s5, 0x4000
	global_load_lds_dwordx4 v188, s[52:53]
	s_mov_b32 m0, s58
	s_add_i32 s59, s5, 0x6000
	global_load_lds_dwordx4 v186, s[12:13]
	s_mov_b32 m0, s59
	v_mov_b32_e32 v191, 0
	global_load_lds_dwordx4 v188, s[12:13]
	v_mov_b32_e32 v187, v191
	v_mov_b32_e32 v189, v191
	s_cmp_eq_u32 s11, 1
	v_lshl_add_u64 v[8:9], s[54:55], 0, v[186:187]
	v_lshl_add_u64 v[6:7], s[54:55], 0, v[188:189]
	v_lshl_add_u64 v[2:3], s[52:53], 0, v[186:187]
	s_cselect_b64 s[12:13], -1, 0
	s_cmp_lg_u32 s11, 1
	v_lshl_add_u64 v[4:5], s[52:53], 0, v[188:189]
	s_cbranch_scc1 .LBB0_1590
	s_barrier

.LBB0_1593:
	s_add_i32 s67, s67, 1
	s_waitcnt lgkmcnt(0)
	s_xor_b32 s78, s67, s77
	s_mul_i32 s43, s78, s60
	s_add_i32 s43, s43, s96
	s_cmpk_lt_i32 s43, 0x200
	s_cselect_b64 s[44:45], -1, 0
	s_cmpk_gt_i32 s43, 0x1ff
	s_cbranch_scc1 .LBB0_1602
	s_add_i32 s42, s43, 0xffffff00
	s_cmpk_lt_i32 s43, 0x100
	s_cselect_b64 s[6:7], -1, 0
	s_and_b64 vcc, exec, s[6:7]
	s_cselect_b32 s56, s43, s42
	s_ashr_i32 s51, s56, 5
	s_cbranch_vccnz .LBB0_1600
	s_cmp_gt_i32 s51, 5
	s_mov_b64 s[46:47], -1
	s_cbranch_scc0 .LBB0_1597
	s_lshl_b32 s42, s51, 2
	s_add_i32 s42, s42, 12
	s_mov_b64 s[46:47], 0
